# v059 + the early layer-1 conversion also takes the down-projection items (separate destination buffer); the tail keeps only the gate/up items
# speedup vs baseline: 1.0403x; 1.0011x over previous
; #define LAS __attribute__((address_space(3)))
; __global__ void __launch_bounds__(512, 2) fwd_mega(Args a) {
;     ...
;     auto convert_items = [&](int LL, int lo, int hi, int w0, int nw_, size_t wd_off) __attribute__((always_inline)) {
;         LAS float* scr = (LAS float*)(lds + wave * 16384);
;         for (int it0 = lo + w0; it0 < hi; it0 += nw_) {
;             int it = it0;
;             if (it < 2688) { const int kb = it / 168, nb = it % 168; tr_item(INF(6) + (size_t)LL * D * INC, INC, WSP(WS_WIN), 1024, 0, 32 * nb, 64 * kb, 32 * nb, scr, lane); continue; } it -= 2688;
;             if (it < 512) { const int kb = it / 32, nb = it % 32; tr_item(INF(13) + (size_t)LL * D * D, D, WSP(WS_PAB), 1024, 0, 32 * nb, 64 * kb, 32 * nb, scr, lane); continue; } it -= 512;
;             if (it < 512) { const int kb = it / 32, nb = it % 32; tr_item(INF(12) + (size_t)LL * D * D, D, WSP(WS_PAB), 1024, 0, 1024 + 32 * nb, 64 * kb, 32 * nb, scr, lane); continue; } it -= 512;
;             if (it < 512) { const int kb = it / 32, nb = it % 32; tr_item(INF(14) + (size_t)LL * D * D, D, WSP(WS_WO2), 1024, 0, 32 * nb, 64 * kb, 32 * nb, scr, lane); continue; } it -= 512;
;             if (it < 1408) { const int kb = it / 88, nb = it % 88, n0 = 32 * nb; tr_item(INF(16) + (size_t)LL * D * FF, FF, WSP(WS_WGU), 1024, 0, (n0 >> 7) * 256 + (n0 & 127), 64 * kb, n0, scr, lane); continue; } it -= 1408;
;             if (it < 1408) { const int kb = it / 88, nb = it % 88, n0 = 32 * nb; tr_item(INF(17) + (size_t)LL * D * FF, FF, WSP(WS_WGU), 1024, 0, (n0 >> 7) * 256 + 128 + (n0 & 127), 64 * kb, n0, scr, lane); continue; } it -= 1408;
;             { const int kb = it / 32, nb = it % 32; tr_item(INF(20) + (size_t)LL * FF * D, D, WSP(wd_off), 2816, 0, 32 * nb, 64 * kb, 32 * nb, scr, lane); }
.Lgc_985:
	s_addk_i32 s53, 0x400
	s_cmpk_lt_i32 s53, 0x1080
	s_cbranch_scc1 .Lgc_l2
	s_cmpk_ge_i32 s53, 0x1b80
	s_cbranch_scc1 .Lgc_l2
	s_addk_i32 s53, 0xb00
.Lgc_l2:
	s_lshl_b32 s4, s53, 5
	s_lshl_b32 s12, s53, 1
	s_cmpk_lt_i32 s53, 0x2100
	s_cbranch_scc0 .Lgc_exit

; #define LAS __attribute__((address_space(3)))
; __global__ void __launch_bounds__(512, 2) fwd_mega(Args a) {
;     ...
;     auto convert_items = [&](int LL, int lo, int hi, int w0, int nw_, size_t wd_off) __attribute__((always_inline)) {
;         LAS float* scr = (LAS float*)(lds + wave * 16384);
;         for (int it0 = lo + w0; it0 < hi; it0 += nw_) {
;             int it = it0;
;             if (it < 2688) { const int kb = it / 168, nb = it % 168; tr_item(INF(6) + (size_t)LL * D * INC, INC, WSP(WS_WIN), 1024, 0, 32 * nb, 64 * kb, 32 * nb, scr, lane); continue; } it -= 2688;
;     ...
;         if constexpr (l + 1 < NL) {
;             __syncthreads();
;             convert_items(l + 1, 0, 8448, gw, NGW, WS_WD1);
;             for (int it = gw; it < 160; it += NGW) sgu_wfrag_item(INF(10) + (size_t)(l + 1) * 8 * 128 * 128, (v4u*)(a.ws + WS_WF), it, lane);
.LBB0_983:
	v_readlane_b32 s4, v246, 4
	v_readlane_b32 s5, v246, 5
	s_andn2_b64 vcc, exec, s[4:5]
	s_barrier
	s_cbranch_vccnz .LBB0_1010
	v_readlane_b32 s4, v247, 40
	v_readlane_b32 s5, v247, 41
	s_nop 4
	s_mov_b64 s[6:7], s[26:27]
	v_lshlrev_b32_e32 v2, 2, v205
	v_mul_u32_u24_e32 v6, 0x84, v200
	v_readlane_b32 s10, v246, 3
	v_mov_b32_e32 v3, 0
	v_mov_b32_e32 v7, v3
	v_add3_u32 v28, s10, v2, v6
	v_and_b32_e32 v6, 56, v204
	v_mul_u32_u24_e32 v8, 0x84, v6
	v_lshlrev_b32_e32 v6, 1, v6
	s_waitcnt lgkmcnt(0)
	v_lshl_add_u64 v[4:5], s[4:5], 0, v[2:3]
	v_lshl_add_u64 v[26:27], s[6:7], 0, v[6:7]
	s_mov_b64 s[4:5], 0xf600000
	v_lshl_add_u64 v[6:7], v[26:27], 0, s[4:5]
	v_readlane_b32 s4, v247, 32
	v_readlane_b32 s5, v247, 33
	v_readlane_b32 s6, v247, 34
	v_readlane_b32 s7, v247, 35
	s_nop 4
	v_lshlrev_b32_e32 v9, 2, v201
	s_mov_b64 s[8:9], 0xb00000
	v_add3_u32 v29, s10, v8, v9
	v_readlane_b32 s10, v247, 28
	v_readlane_b32 s11, v247, 29
	s_nop 4
	s_waitcnt lgkmcnt(0)
	v_lshl_add_u64 v[8:9], s[6:7], 0, v[2:3]
	s_mov_b64 s[6:7], 0x1a80000
	v_lshl_add_u64 v[12:13], s[4:5], 0, v[2:3]
	v_lshl_add_u64 v[4:5], v[4:5], 0, s[8:9]
	v_lshl_add_u64 v[8:9], v[8:9], 0, s[8:9]
	v_lshl_add_u64 v[10:11], v[26:27], 0, s[6:7]
	v_lshl_add_u64 v[12:13], v[12:13], 0, s[8:9]
	v_readlane_b32 s8, v247, 12
	v_readlane_b32 s9, v247, 13
	v_readlane_b32 s4, v247, 24
	v_readlane_b32 s5, v247, 25
	v_readlane_b32 s6, v247, 26
	v_readlane_b32 s7, v247, 27
	s_nop 4
	v_lshl_add_u64 v[14:15], s[10:11], 0, v[2:3]
	s_mov_b64 s[10:11], 0x400000
	s_mov_b64 s[12:13], 0x1680000
	s_waitcnt vmcnt(3) lgkmcnt(0)
	v_lshl_add_u64 v[24:25], s[8:9], 0, v[2:3]
	s_waitcnt vmcnt(1)
	v_lshl_add_u64 v[18:19], s[4:5], 0, v[2:3]
	s_mov_b64 s[4:5], 0x1280000
	v_lshl_add_u64 v[20:21], v[26:27], 0, s[4:5]
	s_mov_b64 s[4:5], 0x1500000
	v_lshl_add_u64 v[22:23], s[6:7], 0, v[2:3]
	v_lshl_add_u64 v[24:25], v[24:25], 0, s[4:5]
	s_mov_b64 s[4:5], 0x800000
	v_or_b32_e32 v30, 8, v201
	v_or_b32_e32 v31, 16, v201
	v_or_b32_e32 v32, 24, v201
	v_lshl_add_u64 v[14:15], v[14:15], 0, s[10:11]
	v_lshl_add_u64 v[16:17], v[26:27], 0, s[12:13]
	v_lshl_add_u64 v[18:19], v[18:19], 0, s[10:11]
	v_lshl_add_u64 v[22:23], v[22:23], 0, s[10:11]
	v_lshl_add_u64 v[26:27], v[26:27], 0, s[4:5]
	s_lshl_b32 s4, s22, 5
	s_lshl_b32 s5, s77, 5
	s_lshl_b32 s12, s22, 1
	s_lshl_b32 s13, s77, 1
	s_mov_b32 s7, 0
	s_movk_i32 s14, 0x7fff
	s_mov_b32 s15, 0xffff0000
	s_movk_i32 s16, 0x5000
	s_mov_b32 s17, 0xb000
	s_mov_b32 s18, 0x10000
	s_mov_b32 s19, 0x16000
	s_mov_b32 s20, 0x1b000
	s_mov_b32 s21, 0x21000
	s_mov_b32 s23, 0x26000
	s_mov_b32 s24, 0x2c000
	s_mov_b32 s25, 0x31000
	s_mov_b32 s28, 0x37000
	s_mov_b32 s29, 0x3c000
	s_mov_b32 s30, 0x42000
	s_mov_b32 s31, 0x47000
	s_mov_b32 s34, 0x4d000
	s_mov_b32 s35, 0x52000
	s_mov_b32 s36, 0x58000
	s_mov_b32 s37, 0x5d000
	s_mov_b32 s38, 0x63000
	s_mov_b32 s39, 0x68000
	s_mov_b32 s40, 0x6e000
	s_mov_b32 s41, 0x73000
	s_mov_b32 s42, 0x79000
	s_mov_b32 s43, 0x7e000
	s_mov_b32 s44, 0x84000
	s_mov_b32 s45, 0x89000
	s_mov_b32 s46, 0x8f000
	s_mov_b32 s47, 0x94000
	s_mov_b32 s48, 0x9a000
	s_mov_b32 s49, 0x9f000
	s_mov_b32 s50, 0xa5000
	s_mov_b32 s51, 0xaa000
	s_movk_i32 s52, 0x5400
	v_add_u32_e32 v33, 0x400, v28
	v_add_u32_e32 v34, 0x800, v28
	v_add_u32_e32 v35, 0xc00, v28
	v_add_u32_e32 v36, 0x1000, v28
	v_add_u32_e32 v37, 0x1400, v28
	v_add_u32_e32 v38, 0x1800, v28
	v_add_u32_e32 v39, 0x1c00, v28
	s_mov_b32 s53, s22
	s_movk_i32 s98, 0x2100
	s_cmpk_lg_u32 s3, 0x100
	s_cbranch_scc1 .Lgc_tail0
	s_movk_i32 s98, 0x1b80
	s_addk_i32 s53, 0x1080
	s_add_i32 s4, s4, 0x21000
	s_addk_i32 s12, 0x2100

; __global__ void __launch_bounds__(512, 2) fwd_mega(Args a) {
;     ...
;         for (int it0 = lo + w0; it0 < hi; it0 += nw_) {
.LBB0_985:
	s_add_i32 s53, s53, s77
	s_add_i32 s4, s4, s5
	s_add_i32 s12, s12, s13
	s_cmp_lt_i32 s53, s98
	s_cbranch_scc0 .LBB0_1010
